# ping-pong attention loop: one lgkmcnt wait per pair of MFMAs in the matrix segments (half as many s_waitcnt)
# speedup vs baseline: 1.0107x; 1.0107x over previous
; template <int KB>
; __device__ __forceinline__ void qkt(f32x16& p0, f32x16& p1, const char* K_lds, int r32, int hi, const bf16x8* qr) {
;     p0 = f32x16{}; p1 = f32x16{};
;     const char* kb[4];
; #pragma unroll
;     for (int dd = 0; dd < 4; ++dd) kb[dd] = K_lds + KB * SHM_K + KSWZ(r32, (dd * 16 + hi * 8) * 2);
; #pragma unroll
;     for (int d0 = 0; d0 < 8; ++d0) { const char* a = kb[d0 & 3] + (d0 >> 2) * 128;
;         bf16x8 b0 = *reinterpret_cast<const bf16x8*>(a);
;         bf16x8 b1 = *reinterpret_cast<const bf16x8*>(a + 32 * 256);
;         p0 = __builtin_amdgcn_mfma_f32_32x32x16_bf16(b0, qr[d0], p0, 0, 0, 0);
;         p1 = __builtin_amdgcn_mfma_f32_32x32x16_bf16(b1, qr[d0], p1, 0, 0, 0); }
; }
; template <int VB>
; __device__ __forceinline__ void pv_tile(f32x16* o, int vb0, bf16x8 pa0, bf16x8 pa1, bf16x8 pa2, bf16x8 pa3) {
;     ...
;     PV_D0(0); PV_D0(1); PV_D0(2); PV_D0(3);
.Lp5_vw_a:
	global_load_dwordx2 v[146:147], v179, s[68:69] offset:-8
	s_add_u32 s98, s16, 0x40000
	s_addc_u32 s99, s17, 0
	global_load_dwordx4 v[130:133], v188, s[98:99]
	s_add_u32 s98, s16, 0x50000
	s_addc_u32 s99, s17, 0
	global_load_dwordx4 v[134:137], v188, s[98:99]
	s_add_u32 s98, s100, 0x40000
	s_addc_u32 s99, s101, 0
	global_load_dwordx4 v[138:141], v188, s[98:99]
	s_add_u32 s98, s100, 0x50000
	s_addc_u32 s99, s101, 0
	global_load_dwordx4 v[142:145], v188, s[98:99]
	ds_read_b128 v[66:69], v199 offset:49152
	ds_read_b128 v[82:85], v199 offset:57344
	ds_read_b128 v[172:175], v200 offset:49152
	ds_read_b128 v[232:235], v200 offset:57344
	ds_read_b128 v[236:239], v201 offset:49152
	ds_read_b128 v[240:243], v201 offset:57344
	ds_read_b128 v[244:247], v202 offset:49152
	s_waitcnt lgkmcnt(5)
	v_mfma_f32_32x32x16_bf16 v[66:81], v[66:69], v[126:129], 0
	v_mfma_f32_32x32x16_bf16 v[82:97], v[82:85], v[126:129], 0
	s_waitcnt lgkmcnt(3)
	v_mfma_f32_32x32x16_bf16 v[66:81], v[172:175], v[122:125], v[66:81]
	ds_read_b128 v[172:175], v202 offset:57344
	v_mfma_f32_32x32x16_bf16 v[82:97], v[232:235], v[122:125], v[82:97]
	ds_read_b128 v[232:235], v199 offset:49280
	s_waitcnt lgkmcnt(3)
	v_mfma_f32_32x32x16_bf16 v[66:81], v[236:239], v[118:121], v[66:81]
	ds_read_b128 v[236:239], v199 offset:57472
	v_mfma_f32_32x32x16_bf16 v[82:97], v[240:243], v[118:121], v[82:97]
	ds_read_b128 v[240:243], v200 offset:49280
	s_waitcnt lgkmcnt(3)
	v_mfma_f32_32x32x16_bf16 v[66:81], v[244:247], v[114:117], v[66:81]
	ds_read_b128 v[244:247], v200 offset:57472
	v_mfma_f32_32x32x16_bf16 v[82:97], v[172:175], v[114:117], v[82:97]
	ds_read_b128 v[172:175], v201 offset:49280
	s_waitcnt lgkmcnt(3)
	v_mfma_f32_32x32x16_bf16 v[66:81], v[232:235], v[110:113], v[66:81]
	ds_read_b128 v[232:235], v201 offset:57472
	v_mfma_f32_32x32x16_bf16 v[82:97], v[236:239], v[110:113], v[82:97]
	ds_read_b128 v[236:239], v202 offset:49280
	s_waitcnt lgkmcnt(3)
	v_mfma_f32_32x32x16_bf16 v[66:81], v[240:243], v[106:109], v[66:81]
	ds_read_b64_tr_b16 v[212:213], v1 offset:0x0
	ds_read_b64_tr_b16 v[214:215], v1 offset:0x800
	ds_read_b64_tr_b16 v[216:217], v1 offset:0x200
	ds_read_b64_tr_b16 v[218:219], v1 offset:0xa00
	ds_read_b64_tr_b16 v[220:221], v1 offset:0x400
	ds_read_b64_tr_b16 v[222:223], v1 offset:0xc00
	ds_read_b64_tr_b16 v[224:225], v1 offset:0x600
	ds_read_b64_tr_b16 v[226:227], v1 offset:0xe00
	ds_read_b128 v[240:243], v202 offset:57472
	v_mfma_f32_32x32x16_bf16 v[82:97], v[244:247], v[106:109], v[82:97]
	s_waitcnt lgkmcnt(10)
	v_mfma_f32_32x32x16_bf16 v[66:81], v[172:175], v[102:105], v[66:81]
	v_mfma_f32_32x32x16_bf16 v[82:97], v[232:235], v[102:105], v[82:97]
	s_waitcnt lgkmcnt(0)
	v_mfma_f32_32x32x16_bf16 v[66:81], v[236:239], v[98:101], v[66:81]
	v_mfma_f32_32x32x16_bf16 v[82:97], v[240:243], v[98:101], v[82:97]
	ds_read_b64_tr_b16 v[248:249], v1 offset:0x1000
	ds_read_b64_tr_b16 v[250:251], v1 offset:0x1800
	ds_read_b64_tr_b16 v[172:173], v1 offset:0x1200
	ds_read_b64_tr_b16 v[174:175], v1 offset:0x1a00
	ds_read_b64_tr_b16 v[232:233], v1 offset:0x1400
	ds_read_b64_tr_b16 v[234:235], v1 offset:0x1c00
	s_waitcnt lgkmcnt(11)
	v_mfma_f32_32x32x16_bf16 v[2:17], v[148:151], v[212:215], v[2:17]
	ds_read_b64_tr_b16 v[236:237], v1 offset:0x1600
	ds_read_b64_tr_b16 v[238:239], v1 offset:0x1e00
	v_mfma_f32_32x32x16_bf16 v[50:65], v[148:151], v[216:219], v[50:65]
	ds_read_b64_tr_b16 v[240:241], v1 offset:0x2000
	ds_read_b64_tr_b16 v[242:243], v1 offset:0x2800
	s_waitcnt lgkmcnt(11)
	v_mfma_f32_32x32x16_bf16 v[34:49], v[148:151], v[220:223], v[34:49]
	ds_read_b64_tr_b16 v[244:245], v1 offset:0x2200
	ds_read_b64_tr_b16 v[246:247], v1 offset:0x2a00
	v_mfma_f32_32x32x16_bf16 v[18:33], v[148:151], v[224:227], v[18:33]
	ds_read_b64_tr_b16 v[224:225], v1 offset:0x2400
	ds_read_b64_tr_b16 v[226:227], v1 offset:0x2c00
	s_waitcnt lgkmcnt(10)
	v_mfma_f32_32x32x16_bf16 v[2:17], v[152:155], v[248:251], v[2:17]
	ds_read_b64_tr_b16 v[248:249], v1 offset:0x2600
	ds_read_b64_tr_b16 v[250:251], v1 offset:0x2e00
	v_mfma_f32_32x32x16_bf16 v[50:65], v[152:155], v[172:175], v[50:65]
	ds_read_b64_tr_b16 v[172:173], v1 offset:0x3000
	ds_read_b64_tr_b16 v[174:175], v1 offset:0x3800
	s_waitcnt lgkmcnt(10)
	v_mfma_f32_32x32x16_bf16 v[34:49], v[152:155], v[232:235], v[34:49]
	ds_read_b64_tr_b16 v[232:233], v1 offset:0x3200
	ds_read_b64_tr_b16 v[234:235], v1 offset:0x3a00
	v_mfma_f32_32x32x16_bf16 v[18:33], v[152:155], v[236:239], v[18:33]
	ds_read_b64_tr_b16 v[236:237], v1 offset:0x3400
	ds_read_b64_tr_b16 v[238:239], v1 offset:0x3c00
	s_waitcnt lgkmcnt(10)
	v_mfma_f32_32x32x16_bf16 v[2:17], v[156:159], v[240:243], v[2:17]
	ds_read_b64_tr_b16 v[240:241], v1 offset:0x3600
	ds_read_b64_tr_b16 v[242:243], v1 offset:0x3e00
	v_mfma_f32_32x32x16_bf16 v[50:65], v[156:159], v[244:247], v[50:65]
	s_waitcnt lgkmcnt(8)
	v_mfma_f32_32x32x16_bf16 v[34:49], v[156:159], v[224:227], v[34:49]
	v_mfma_f32_32x32x16_bf16 v[18:33], v[156:159], v[248:251], v[18:33]
	s_waitcnt lgkmcnt(4)
	v_mfma_f32_32x32x16_bf16 v[2:17], v[208:211], v[172:175], v[2:17]
	v_mfma_f32_32x32x16_bf16 v[50:65], v[208:211], v[232:235], v[50:65]
	s_waitcnt lgkmcnt(0)
	v_mfma_f32_32x32x16_bf16 v[34:49], v[208:211], v[236:239], v[34:49]
	v_mfma_f32_32x32x16_bf16 v[18:33], v[208:211], v[240:243], v[18:33]
	s_waitcnt vmcnt(0)
	ds_write_b128 v204, v[138:141] offset:32768
	ds_write_b128 v204, v[142:145] offset:40960
	s_waitcnt lgkmcnt(0)
	s_barrier
; __device__ __forceinline__ void sel_mask_tile(f32x16& p0, f32x16& p1, unsigned wlo, unsigned whi, int hi) {
;     const unsigned NEGB = 0xff800000u;
;     const unsigned lo = wlo >> (4 * hi), h2 = whi >> (4 * hi);
; #pragma unroll
;     for (int r = 0; r < 16; ++r) {
;         const int c = (r & 3) + 8 * (r >> 2);
;         const unsigned m0 = (unsigned)__builtin_amdgcn_sbfe((int)lo, c, 1), m1 = (unsigned)__builtin_amdgcn_sbfe((int)h2, c, 1);
;         p0[r] = __uint_as_float((__float_as_uint(p0[r]) & m0) | (NEGB & ~m0));
;         p1[r] = __uint_as_float((__float_as_uint(p1[r]) & m1) | (NEGB & ~m1));
;     }
; }
; __device__ __forceinline__ void partialSM(f32x16& p0, f32x16& p1, float& m_reg, float& mn, float& alpha) {
;     float pmax = p0[0];
; #pragma unroll
;     for (int r = 1; r < 16; ++r) pmax = fmaxf(pmax, p0[r]);
; #pragma unroll
;     for (int r = 0; r < 16; ++r) pmax = fmaxf(pmax, p1[r]);
;     { auto rr = __builtin_amdgcn_permlane32_swap(__float_as_uint(pmax), __float_as_uint(pmax), false, false);
;       pmax = fmaxf(__uint_as_float(rr[0]), __uint_as_float(rr[1])); }
;     constexpr float C2 = 1.4426950408889634f * SCALE;
;     if (__builtin_expect(__all((pmax - m_reg) * SCALE <= THR), 1)) { mn = m_reg; alpha = 1.f; }
;     else { mn = fmaxf(m_reg, pmax); alpha = __builtin_amdgcn_exp2f((m_reg - mn) * C2); m_reg = mn; }
	s_nop 0
	s_waitcnt vmcnt(4)
	v_lshrrev_b32_e32 v160, v163, v146
	v_lshrrev_b32_e32 v161, v163, v147
	v_bfe_i32 v146, v160, 0, 1
	v_bfe_i32 v147, v161, 0, 1
	v_bitop3_b32 v146, v66, s74, v146 bitop3:0xe4
	v_bitop3_b32 v66, v82, s74, v147 bitop3:0xe4
	v_bfe_i32 v82, v160, 1, 1
	v_bfe_i32 v147, v161, 1, 1
	v_bitop3_b32 v82, v67, s74, v82 bitop3:0xe4
	v_bitop3_b32 v67, v83, s74, v147 bitop3:0xe4
	v_bfe_i32 v83, v160, 2, 1
	v_bfe_i32 v147, v161, 2, 1
	v_bitop3_b32 v83, v68, s74, v83 bitop3:0xe4
	v_bitop3_b32 v68, v84, s74, v147 bitop3:0xe4
	v_bfe_i32 v84, v160, 3, 1
	v_bfe_i32 v148, v161, 3, 1
	v_bitop3_b32 v147, v69, s74, v84 bitop3:0xe4
	v_bfe_i32 v84, v160, 8, 1
	v_bitop3_b32 v69, v85, s74, v148 bitop3:0xe4
	v_bfe_i32 v85, v161, 8, 1
	v_bitop3_b32 v148, v70, s74, v84 bitop3:0xe4
	v_bfe_i32 v84, v160, 9, 1
	v_bitop3_b32 v70, v86, s74, v85 bitop3:0xe4
	v_bfe_i32 v85, v161, 9, 1
	v_bitop3_b32 v149, v71, s74, v84 bitop3:0xe4
	v_bfe_i32 v84, v160, 10, 1
	v_bitop3_b32 v71, v87, s74, v85 bitop3:0xe4
	v_bfe_i32 v85, v161, 10, 1
	v_bitop3_b32 v87, v72, s74, v84 bitop3:0xe4
	v_bfe_i32 v84, v160, 11, 1
	v_bitop3_b32 v72, v88, s74, v85 bitop3:0xe4
	v_bfe_i32 v85, v161, 11, 1
	v_bitop3_b32 v88, v73, s74, v84 bitop3:0xe4
	v_bfe_i32 v73, v160, 16, 1
	v_bitop3_b32 v84, v89, s74, v85 bitop3:0xe4
	v_bfe_i32 v85, v161, 16, 1
	v_bitop3_b32 v89, v74, s74, v73 bitop3:0xe4
	v_bfe_i32 v73, v160, 17, 1
	v_bfe_i32 v74, v161, 17, 1
	v_bitop3_b32 v85, v90, s74, v85 bitop3:0xe4
	v_bitop3_b32 v90, v75, s74, v73 bitop3:0xe4
	v_bitop3_b32 v86, v91, s74, v74 bitop3:0xe4
	v_bfe_i32 v73, v160, 18, 1
	v_bfe_i32 v74, v161, 18, 1
	v_bitop3_b32 v91, v76, s74, v73 bitop3:0xe4
	v_bitop3_b32 v76, v92, s74, v74 bitop3:0xe4
	v_bfe_i32 v73, v160, 19, 1
	v_bfe_i32 v74, v161, 19, 1
	v_bitop3_b32 v92, v77, s74, v73 bitop3:0xe4
	v_bitop3_b32 v77, v93, s74, v74 bitop3:0xe4
	v_bfe_i32 v73, v160, 24, 1
	v_bfe_i32 v74, v161, 24, 1
	v_bitop3_b32 v93, v78, s74, v73 bitop3:0xe4
	v_bitop3_b32 v78, v94, s74, v74 bitop3:0xe4
	v_bfe_i32 v73, v160, 25, 1
	v_bfe_i32 v74, v161, 25, 1
	v_bitop3_b32 v79, v79, s74, v73 bitop3:0xe4
	v_bitop3_b32 v73, v95, s74, v74 bitop3:0xe4
	v_bfe_i32 v74, v160, 26, 1
	v_bfe_i32 v75, v161, 26, 1
	v_bitop3_b32 v80, v80, s74, v74 bitop3:0xe4
	v_bitop3_b32 v74, v96, s74, v75 bitop3:0xe4
	v_bfe_i32 v75, v160, 27, 1
	v_bfe_i32 v94, v161, 27, 1
	v_bitop3_b32 v81, v81, s74, v75 bitop3:0xe4
	v_bitop3_b32 v75, v97, s74, v94 bitop3:0xe4
	v_max_f32_e32 v94, v146, v82
	v_max3_f32 v94, v94, v83, v147
	v_max3_f32 v94, v94, v148, v149
	v_max3_f32 v94, v94, v87, v88
	v_max3_f32 v94, v94, v89, v90
	v_max3_f32 v94, v94, v91, v92
	v_max3_f32 v94, v94, v93, v79
	v_max3_f32 v94, v94, v80, v81
	v_max3_f32 v94, v94, v66, v67
	v_max3_f32 v94, v94, v68, v69
	v_max3_f32 v94, v94, v70, v71
	v_max3_f32 v94, v94, v72, v84
	v_max3_f32 v94, v94, v85, v86
	v_max3_f32 v94, v94, v76, v77
	v_max3_f32 v94, v94, v78, v73
	v_max3_f32 v94, v94, v74, v75
	v_mov_b32_e32 v95, v94
	s_nop 1
	v_permlane32_swap_b32_e32 v94, v95
	v_max_f32_e32 v94, v94, v95
	v_sub_f32_e32 v95, v94, v206
	v_mul_f32_e32 v95, 0x3db504f3, v95
	v_cmp_ge_f32_e32 vcc, s75, v95
	s_cmp_eq_u64 vcc, exec
	s_cselect_b64 s[6:7], -1, 0
	s_cbranch_scc1 .Lp5_b1fast
	v_max_f32_e32 v94, v206, v94
	v_sub_f32_e32 v96, v206, v94
	v_mul_f32_e32 v96, 0x3e0293ee, v96
	v_exp_f32_e32 v96, v96

; template <int KB>
; __device__ __forceinline__ void qkt(f32x16& p0, f32x16& p1, const char* K_lds, int r32, int hi, const bf16x8* qr) {
;     p0 = f32x16{}; p1 = f32x16{};
;     const char* kb[4];
; #pragma unroll
;     for (int dd = 0; dd < 4; ++dd) kb[dd] = K_lds + KB * SHM_K + KSWZ(r32, (dd * 16 + hi * 8) * 2);
; #pragma unroll
;     for (int d0 = 0; d0 < 8; ++d0) { const char* a = kb[d0 & 3] + (d0 >> 2) * 128;
;         bf16x8 b0 = *reinterpret_cast<const bf16x8*>(a);
;         bf16x8 b1 = *reinterpret_cast<const bf16x8*>(a + 32 * 256);
;         p0 = __builtin_amdgcn_mfma_f32_32x32x16_bf16(b0, qr[d0], p0, 0, 0, 0);
;         p1 = __builtin_amdgcn_mfma_f32_32x32x16_bf16(b1, qr[d0], p1, 0, 0, 0); }
; }
; template <int VB>
; __device__ __forceinline__ void pv_tile(f32x16* o, int vb0, bf16x8 pa0, bf16x8 pa1, bf16x8 pa2, bf16x8 pa3) {
;     ...
;     PV_D0(0); PV_D0(1); PV_D0(2); PV_D0(3);
.Lp5_a2:
	ds_read_b128 v[66:69], v199 offset:32768
	ds_read_b128 v[70:73], v199 offset:40960
	ds_read_b128 v[172:175], v200 offset:32768
	ds_read_b128 v[224:227], v200 offset:40960
	ds_read_b128 v[232:235], v201 offset:32768
	ds_read_b128 v[236:239], v201 offset:40960
	ds_read_b128 v[240:243], v202 offset:32768
	ds_read_b128 v[244:247], v202 offset:40960
	s_waitcnt lgkmcnt(6)
	v_mfma_f32_32x32x16_bf16 v[82:97], v[66:69], v[126:129], 0
	v_mfma_f32_32x32x16_bf16 v[66:81], v[70:73], v[126:129], 0
	s_waitcnt lgkmcnt(4)
	v_mfma_f32_32x32x16_bf16 v[82:97], v[172:175], v[122:125], v[82:97]
	ds_read_b128 v[172:175], v199 offset:32896
	v_mfma_f32_32x32x16_bf16 v[66:81], v[224:227], v[122:125], v[66:81]
	ds_read_b128 v[224:227], v199 offset:41088
	s_waitcnt lgkmcnt(4)
	v_mfma_f32_32x32x16_bf16 v[82:97], v[232:235], v[118:121], v[82:97]
	ds_read_b128 v[232:235], v200 offset:32896
	v_mfma_f32_32x32x16_bf16 v[66:81], v[236:239], v[118:121], v[66:81]
	ds_read_b128 v[236:239], v200 offset:41088
	s_waitcnt lgkmcnt(4)
	v_mfma_f32_32x32x16_bf16 v[82:97], v[240:243], v[114:117], v[82:97]
	ds_read_b128 v[240:243], v201 offset:32896
	v_mfma_f32_32x32x16_bf16 v[66:81], v[244:247], v[114:117], v[66:81]
	ds_read_b128 v[244:247], v201 offset:41088
	s_waitcnt lgkmcnt(4)
	v_mfma_f32_32x32x16_bf16 v[82:97], v[172:175], v[110:113], v[82:97]
	ds_read_b128 v[172:175], v202 offset:32896
	v_mfma_f32_32x32x16_bf16 v[66:81], v[224:227], v[110:113], v[66:81]
	ds_read_b128 v[224:227], v202 offset:41088
	s_waitcnt lgkmcnt(4)
	v_mfma_f32_32x32x16_bf16 v[82:97], v[232:235], v[106:109], v[82:97]
	ds_read_b64_tr_b16 v[212:213], v1 offset:0x4000
	ds_read_b64_tr_b16 v[214:215], v1 offset:0x4800
	ds_read_b64_tr_b16 v[216:217], v1 offset:0x4200
	ds_read_b64_tr_b16 v[218:219], v1 offset:0x4a00
	ds_read_b64_tr_b16 v[220:221], v1 offset:0x4400
	ds_read_b64_tr_b16 v[222:223], v1 offset:0x4c00
	ds_read_b64_tr_b16 v[248:249], v1 offset:0x4600
	ds_read_b64_tr_b16 v[250:251], v1 offset:0x4e00
	v_mfma_f32_32x32x16_bf16 v[66:81], v[236:239], v[106:109], v[66:81]
	s_waitcnt lgkmcnt(10)
	v_mfma_f32_32x32x16_bf16 v[82:97], v[240:243], v[102:105], v[82:97]
	v_mfma_f32_32x32x16_bf16 v[66:81], v[244:247], v[102:105], v[66:81]
	s_waitcnt lgkmcnt(8)
	v_mfma_f32_32x32x16_bf16 v[82:97], v[172:175], v[98:101], v[82:97]
	v_mfma_f32_32x32x16_bf16 v[66:81], v[224:227], v[98:101], v[66:81]
	s_add_i32 s82, s82, 2
	s_cmp_le_u32 s82, s81
	s_cselect_b64 s[36:37], -1, 0
	s_cselect_b32 s76, 1, 0
	s_cmp_gt_u32 s82, s81
	s_cbranch_scc1 .Lp5_skip_ld
.LBB0_1305:
	ds_read_b64_tr_b16 v[172:173], v1 offset:0x5000
	ds_read_b64_tr_b16 v[174:175], v1 offset:0x5800
	ds_read_b64_tr_b16 v[224:225], v1 offset:0x5200
	ds_read_b64_tr_b16 v[226:227], v1 offset:0x5a00
	ds_read_b64_tr_b16 v[232:233], v1 offset:0x5400
	ds_read_b64_tr_b16 v[234:235], v1 offset:0x5c00
	s_waitcnt lgkmcnt(10)
	v_mfma_f32_32x32x16_bf16 v[2:17], v[146:149], v[212:215], v[2:17]
	ds_read_b64_tr_b16 v[236:237], v1 offset:0x5600
	ds_read_b64_tr_b16 v[238:239], v1 offset:0x5e00
	v_mfma_f32_32x32x16_bf16 v[50:65], v[146:149], v[216:219], v[50:65]
	ds_read_b64_tr_b16 v[240:241], v1 offset:0x6000
	ds_read_b64_tr_b16 v[242:243], v1 offset:0x6800
	s_waitcnt lgkmcnt(10)
	v_mfma_f32_32x32x16_bf16 v[34:49], v[146:149], v[220:223], v[34:49]
	ds_read_b64_tr_b16 v[244:245], v1 offset:0x6200
	ds_read_b64_tr_b16 v[246:247], v1 offset:0x6a00
	v_mfma_f32_32x32x16_bf16 v[18:33], v[146:149], v[248:251], v[18:33]
	ds_read_b64_tr_b16 v[248:249], v1 offset:0x6400
	ds_read_b64_tr_b16 v[250:251], v1 offset:0x6c00
	s_waitcnt lgkmcnt(10)
	v_mfma_f32_32x32x16_bf16 v[2:17], v[150:153], v[172:175], v[2:17]
	ds_read_b64_tr_b16 v[172:173], v1 offset:0x6600
	ds_read_b64_tr_b16 v[174:175], v1 offset:0x6e00
	v_mfma_f32_32x32x16_bf16 v[50:65], v[150:153], v[224:227], v[50:65]
	ds_read_b64_tr_b16 v[224:225], v1 offset:0x7000
	ds_read_b64_tr_b16 v[226:227], v1 offset:0x7800
	s_waitcnt lgkmcnt(10)
	v_mfma_f32_32x32x16_bf16 v[34:49], v[150:153], v[232:235], v[34:49]
	ds_read_b64_tr_b16 v[232:233], v1 offset:0x7200
	ds_read_b64_tr_b16 v[234:235], v1 offset:0x7a00
	v_mfma_f32_32x32x16_bf16 v[18:33], v[150:153], v[236:239], v[18:33]
	ds_read_b64_tr_b16 v[236:237], v1 offset:0x7400
	ds_read_b64_tr_b16 v[238:239], v1 offset:0x7c00
	s_waitcnt lgkmcnt(10)
	v_mfma_f32_32x32x16_bf16 v[2:17], v[154:157], v[240:243], v[2:17]
	ds_read_b64_tr_b16 v[240:241], v1 offset:0x7600
	ds_read_b64_tr_b16 v[242:243], v1 offset:0x7e00
	v_mfma_f32_32x32x16_bf16 v[50:65], v[154:157], v[244:247], v[50:65]
	s_waitcnt lgkmcnt(8)
	v_mfma_f32_32x32x16_bf16 v[34:49], v[154:157], v[248:251], v[34:49]
	v_mfma_f32_32x32x16_bf16 v[18:33], v[154:157], v[172:175], v[18:33]
	s_waitcnt lgkmcnt(4)
	v_mfma_f32_32x32x16_bf16 v[2:17], v[158:161], v[224:227], v[2:17]
	v_mfma_f32_32x32x16_bf16 v[50:65], v[158:161], v[232:235], v[50:65]
	s_waitcnt lgkmcnt(0)
	v_mfma_f32_32x32x16_bf16 v[34:49], v[158:161], v[236:239], v[34:49]
	v_mfma_f32_32x32x16_bf16 v[18:33], v[158:161], v[240:243], v[18:33]
	s_cmp_eq_u64 s[36:37], 0
	s_cbranch_scc1 .Lp5_kw2_skip
	s_waitcnt vmcnt(0)
	ds_write_b128 v204, v[138:141] offset:49152
	ds_write_b128 v204, v[142:145] offset:57344
